# static s_setprio 1 for waves 4-7 inside the select sweep bodies
# speedup vs baseline: 1.0022x; 1.0022x over previous
; template <int PASS> ...
;     ...
;         for (int e = 0; e < 8; ++e) { const unsigned char* tp = lp + (hb * 8 + e) * 2048; kf[e][0] = *(const h16x8*)(tp + ((fq ^ sw) << 4)); kf[e][1] = *(const h16x8*)(tp + (((fq + 4) ^ sw) << 4)); }
; #pragma unroll
;         for (int e = 0; e < 8; ++e) { const int T = Tbase + hb * 8 + e;
;             f32x4 a0 = (f32x4){0.f, 0.f, 0.f, 0.f}, a1 = a0;
;             a0 = __builtin_amdgcn_mfma_f32_16x16x32_f16(aq[0][0], kf[e][0], a0, 0, 0, 0); a0 = __builtin_amdgcn_mfma_f32_16x16x32_f16(aq[0][1], kf[e][1], a0, 0, 0, 0);
;             a1 = __builtin_amdgcn_mfma_f32_16x16x32_f16(aq[1][0], kf[e][0], a1, 0, 0, 0); a1 = __builtin_amdgcn_mfma_f32_16x16x32_f16(aq[1][1], kf[e][1], a1, 0, 0, 0);
;             const h16x2 z2 = (h16x2){(h16)0.f, (h16)0.f};
;             const h16x2 r0 = __builtin_elementwise_max(__builtin_bit_cast(h16x2, __builtin_amdgcn_cvt_pkrtz(a0[0], a0[1])), z2), r1 = __builtin_elementwise_max(__builtin_bit_cast(h16x2, __builtin_amdgcn_cvt_pkrtz(a0[2], a0[3])), z2);
;             const h16x2 r2 = __builtin_elementwise_max(__builtin_bit_cast(h16x2, __builtin_amdgcn_cvt_pkrtz(a1[0], a1[1])), z2), r3 = __builtin_elementwise_max(__builtin_bit_cast(h16x2, __builtin_amdgcn_cvt_pkrtz(a1[2], a1[3])), z2);
;             const float sa = __builtin_amdgcn_fdot2(r0, wp[0], __builtin_amdgcn_fdot2(r1, wp[1], __builtin_amdgcn_fdot2(r2, wp[2], __builtin_amdgcn_fdot2(r3, wp[3], 0.f, false), false), false), false);
;             const int key = 16 * T + fr;
;             if (key <= tq) {
;                 const unsigned bin = (unsigned)(int)fminf(fmaxf(sa * 32.f + 128.f, 0.f), 255.f);
;                 if (PASS == 1) { if (bin >= b0) atomicAdd(&myhist[fq * 256 + bin], 1u); }
; __device__ __forceinline__ void dsa_select(const h16* PROJ, unsigned short* IDX, int* CNT, unsigned char* shm, unsigned* bar, unsigned xcc, unsigned xrank) {
;     ...
;             float wv[8];
;             { const h16x8 w8 = *(const h16x8*)(PROJ + O_WI + (size_t)(tokbase + tq) * 8);
; #pragma unroll
;               for (int h = 0; h < 8; ++h) wv[h] = (float)w8[h] * 0.04419417382415922f; }
;             h16x2 wp[4];
; #pragma unroll
;             for (int h = 0; h < 4; ++h) { wp[h].x = (h16)wv[(h >> 1) * 4 + (h & 1) * 2]; wp[h].y = (h16)wv[(h >> 1) * 4 + (h & 1) * 2 + 1]; }
.LBB0_182:
	v_cmp_lt_u32_e32 vcc, 0xff, v160
	s_cbranch_vccz .Lp1_noprio
	s_setprio 1
.Lp1_noprio:
	s_and_b32 s62, s4, 0x8000
	v_add_u32_e32 v64, s62, v134
	v_add_u32_e32 v122, v64, v135
	v_add_u32_e32 v123, v64, v136
	v_lshlrev_b32_e32 v121, 8, v121
	v_sub_u32_e32 v121, v115, v121
	v_sub_u32_e32 v78, v192, v121
	v_cmp_le_i32_e32 vcc, 0, v78
	s_cmp_eq_u64 vcc, -1
	s_cbranch_scc1 .Lp1_interior
	ds_read_b128 v[32:35], v122
	ds_read_b128 v[36:39], v123
	ds_read_b128 v[40:43], v122 offset:2048
	ds_read_b128 v[44:47], v123 offset:2048
	v_mov_b32_e32 v79, 0x437f0000
	v_mul_f32_e32 v88, v106, v106
	v_fmac_f32_e32 v88, v107, v107
	v_fmac_f32_e32 v88, v108, v108
	v_fmac_f32_e32 v88, v109, v109
	v_fmac_f32_e32 v88, v110, v110
	v_fmac_f32_e32 v88, v111, v111
	v_fmac_f32_e32 v88, v112, v112
	v_fmac_f32_e32 v88, v113, v113
	v_max_f32_e32 v88, 0x358637bd, v88
	v_rsq_f32_e32 v88, v88
	s_mov_b32 s62, 0x100001
	s_mov_b32 s63, 0x10000100
	v_mul_f32_e32 v88, 4.0, v88
	v_cvt_pkrtz_f16_f32 v88, v88, v88
	v_pk_mul_f16 v80, v193, v88
	v_pk_mul_f16 v81, v194, v88
	v_pk_mul_f16 v82, v195, v88
	v_pk_mul_f16 v83, v196, v88
	v_cndmask_b32_e64 v80, 0, v80, s[62:63]
	v_cndmask_b32_e64 v81, 0, v81, s[62:63]
	v_cndmask_b32_e64 v82, 0, v82, s[62:63]
	v_cndmask_b32_e64 v83, 0, v83, s[62:63]
	v_mov_b32_e32 v84, 0x43000000
	v_mov_b32_e32 v85, 0
	v_mov_b32_e32 v86, 0
	v_mov_b32_e32 v87, 0
	s_waitcnt lgkmcnt(2)
	v_mfma_f32_16x16x32_f16 v[48:51], v[0:3], v[32:35], 0
	v_mfma_f32_16x16x32_f16 v[52:55], v[8:11], v[32:35], 0
	v_mfma_f32_16x16x32_f16 v[48:51], v[4:7], v[36:39], v[48:51]
	v_mfma_f32_16x16x32_f16 v[52:55], v[12:15], v[36:39], v[52:55]
	s_nop 3
	ds_read_b128 v[32:35], v122 offset:4096
	ds_read_b128 v[36:39], v123 offset:4096
	s_waitcnt lgkmcnt(2)
	v_mfma_f32_16x16x32_f16 v[56:59], v[0:3], v[40:43], 0
	v_cvt_pkrtz_f16_f32 v67, v54, v55
	v_cvt_pkrtz_f16_f32 v66, v52, v53
	v_pk_max_f16 v67, v67, 0
	v_pk_max_f16 v66, v66, 0
	v_mfma_f32_16x16x32_f16 v[60:63], v[8:11], v[40:43], 0
	v_cvt_pkrtz_f16_f32 v65, v50, v51
	v_cvt_pkrtz_f16_f32 v64, v48, v49
	v_pk_max_f16 v65, v65, 0
	v_mfma_f32_16x16x32_f16 v[56:59], v[4:7], v[44:47], v[56:59]
	v_pk_max_f16 v64, v64, 0
	v_mfma_f32_16x16x32_f16 v[60:63], v[12:15], v[44:47], v[60:63]
	s_nop 3
	v_mfma_f32_16x16x32_f16 v[68:71], v[80:83], v[64:67], v[84:87]
	ds_read_b128 v[40:43], v122 offset:6144
	ds_read_b128 v[44:47], v123 offset:6144
	s_waitcnt lgkmcnt(2)
	v_mfma_f32_16x16x32_f16 v[48:51], v[0:3], v[32:35], 0
	v_cvt_pkrtz_f16_f32 v67, v62, v63
	v_cvt_pkrtz_f16_f32 v66, v60, v61
	v_pk_max_f16 v67, v67, 0
	v_pk_max_f16 v66, v66, 0
	v_mfma_f32_16x16x32_f16 v[52:55], v[8:11], v[32:35], 0
	v_cvt_pkrtz_f16_f32 v65, v58, v59
	v_cvt_pkrtz_f16_f32 v64, v56, v57
	v_med3_f32 v76, v68, 0, v79
	v_pk_max_f16 v65, v65, 0
	v_mfma_f32_16x16x32_f16 v[48:51], v[4:7], v[36:39], v[48:51]
	v_pk_max_f16 v64, v64, 0
	v_cvt_u32_f32_e32 v76, v76
	v_cmp_le_i32_e32 vcc, -240, v78
	v_mfma_f32_16x16x32_f16 v[52:55], v[12:15], v[36:39], v[52:55]
	v_lshl_add_u32 v77, v76, 2, v139
	s_and_b64 exec, exec, vcc
	ds_add_u32 v77, v212
	s_mov_b64 exec, -1
	v_mfma_f32_16x16x32_f16 v[72:75], v[80:83], v[64:67], v[84:87]
	ds_read_b128 v[32:35], v122 offset:8192
	ds_read_b128 v[36:39], v123 offset:8192
	s_waitcnt lgkmcnt(3)
	v_mfma_f32_16x16x32_f16 v[56:59], v[0:3], v[40:43], 0
	v_cvt_pkrtz_f16_f32 v67, v54, v55
	v_cvt_pkrtz_f16_f32 v66, v52, v53
	v_pk_max_f16 v67, v67, 0
	v_pk_max_f16 v66, v66, 0
	v_mfma_f32_16x16x32_f16 v[60:63], v[8:11], v[40:43], 0
	v_cvt_pkrtz_f16_f32 v65, v50, v51
	v_cvt_pkrtz_f16_f32 v64, v48, v49
	v_med3_f32 v76, v72, 0, v79
	v_pk_max_f16 v65, v65, 0
	v_mfma_f32_16x16x32_f16 v[56:59], v[4:7], v[44:47], v[56:59]
	v_pk_max_f16 v64, v64, 0
	v_cvt_u32_f32_e32 v76, v76
	v_cmp_le_i32_e32 vcc, -224, v78
	v_mfma_f32_16x16x32_f16 v[60:63], v[12:15], v[44:47], v[60:63]
	v_lshl_add_u32 v77, v76, 2, v139
	s_and_b64 exec, exec, vcc
	ds_add_u32 v77, v212
	s_mov_b64 exec, -1
	v_mfma_f32_16x16x32_f16 v[68:71], v[80:83], v[64:67], v[84:87]
	ds_read_b128 v[40:43], v122 offset:10240
	ds_read_b128 v[44:47], v123 offset:10240
	s_waitcnt lgkmcnt(3)
	v_mfma_f32_16x16x32_f16 v[48:51], v[0:3], v[32:35], 0
	v_cvt_pkrtz_f16_f32 v67, v62, v63
	v_cvt_pkrtz_f16_f32 v66, v60, v61
	v_pk_max_f16 v67, v67, 0
	v_pk_max_f16 v66, v66, 0
	v_mfma_f32_16x16x32_f16 v[52:55], v[8:11], v[32:35], 0
	v_cvt_pkrtz_f16_f32 v65, v58, v59
	v_cvt_pkrtz_f16_f32 v64, v56, v57
	v_med3_f32 v76, v68, 0, v79
	v_pk_max_f16 v65, v65, 0
	v_mfma_f32_16x16x32_f16 v[48:51], v[4:7], v[36:39], v[48:51]
	v_pk_max_f16 v64, v64, 0
	v_cvt_u32_f32_e32 v76, v76
	v_cmp_le_i32_e32 vcc, -208, v78
	v_mfma_f32_16x16x32_f16 v[52:55], v[12:15], v[36:39], v[52:55]
	v_lshl_add_u32 v77, v76, 2, v139
	s_and_b64 exec, exec, vcc
	ds_add_u32 v77, v212
	s_mov_b64 exec, -1
	v_mfma_f32_16x16x32_f16 v[72:75], v[80:83], v[64:67], v[84:87]
	ds_read_b128 v[32:35], v122 offset:12288
	ds_read_b128 v[36:39], v123 offset:12288
	s_waitcnt lgkmcnt(3)
	v_mfma_f32_16x16x32_f16 v[56:59], v[0:3], v[40:43], 0
	v_cvt_pkrtz_f16_f32 v67, v54, v55
	v_cvt_pkrtz_f16_f32 v66, v52, v53
	v_pk_max_f16 v67, v67, 0
	v_pk_max_f16 v66, v66, 0
	v_mfma_f32_16x16x32_f16 v[60:63], v[8:11], v[40:43], 0
	v_cvt_pkrtz_f16_f32 v65, v50, v51
	v_cvt_pkrtz_f16_f32 v64, v48, v49
	v_med3_f32 v76, v72, 0, v79
	v_pk_max_f16 v65, v65, 0
	v_mfma_f32_16x16x32_f16 v[56:59], v[4:7], v[44:47], v[56:59]
	v_pk_max_f16 v64, v64, 0
	v_cvt_u32_f32_e32 v76, v76
	v_cmp_le_i32_e32 vcc, -192, v78
	v_mfma_f32_16x16x32_f16 v[60:63], v[12:15], v[44:47], v[60:63]
	v_lshl_add_u32 v77, v76, 2, v139
	s_and_b64 exec, exec, vcc
	ds_add_u32 v77, v212
	s_mov_b64 exec, -1
	v_mfma_f32_16x16x32_f16 v[68:71], v[80:83], v[64:67], v[84:87]
	ds_read_b128 v[40:43], v122 offset:14336
	ds_read_b128 v[44:47], v123 offset:14336
	s_waitcnt lgkmcnt(3)
; template <int PASS> ...
;     ...
;         for (int e = 0; e < 8; ++e) { const unsigned char* tp = lp + (hb * 8 + e) * 2048; kf[e][0] = *(const h16x8*)(tp + ((fq ^ sw) << 4)); kf[e][1] = *(const h16x8*)(tp + (((fq + 4) ^ sw) << 4)); }
; #pragma unroll
;         for (int e = 0; e < 8; ++e) { const int T = Tbase + hb * 8 + e;
;             f32x4 a0 = (f32x4){0.f, 0.f, 0.f, 0.f}, a1 = a0;
;             a0 = __builtin_amdgcn_mfma_f32_16x16x32_f16(aq[0][0], kf[e][0], a0, 0, 0, 0); a0 = __builtin_amdgcn_mfma_f32_16x16x32_f16(aq[0][1], kf[e][1], a0, 0, 0, 0);
;             a1 = __builtin_amdgcn_mfma_f32_16x16x32_f16(aq[1][0], kf[e][0], a1, 0, 0, 0); a1 = __builtin_amdgcn_mfma_f32_16x16x32_f16(aq[1][1], kf[e][1], a1, 0, 0, 0);
;             const h16x2 z2 = (h16x2){(h16)0.f, (h16)0.f};
;             const h16x2 r0 = __builtin_elementwise_max(__builtin_bit_cast(h16x2, __builtin_amdgcn_cvt_pkrtz(a0[0], a0[1])), z2), r1 = __builtin_elementwise_max(__builtin_bit_cast(h16x2, __builtin_amdgcn_cvt_pkrtz(a0[2], a0[3])), z2);
;             const h16x2 r2 = __builtin_elementwise_max(__builtin_bit_cast(h16x2, __builtin_amdgcn_cvt_pkrtz(a1[0], a1[1])), z2), r3 = __builtin_elementwise_max(__builtin_bit_cast(h16x2, __builtin_amdgcn_cvt_pkrtz(a1[2], a1[3])), z2);
;             const float sa = __builtin_amdgcn_fdot2(r0, wp[0], __builtin_amdgcn_fdot2(r1, wp[1], __builtin_amdgcn_fdot2(r2, wp[2], __builtin_amdgcn_fdot2(r3, wp[3], 0.f, false), false), false), false);
;             const int key = 16 * T + fr;
;             if (key <= tq) {
;                 const unsigned bin = (unsigned)(int)fminf(fmaxf(sa * 32.f + 128.f, 0.f), 255.f);
;                 if (PASS == 1) { if (bin >= b0) atomicAdd(&myhist[fq * 256 + bin], 1u); }
	v_mfma_f32_16x16x32_f16 v[48:51], v[0:3], v[32:35], 0
	v_cvt_pkrtz_f16_f32 v67, v62, v63
	v_cvt_pkrtz_f16_f32 v66, v60, v61
	v_pk_max_f16 v67, v67, 0
	v_pk_max_f16 v66, v66, 0
	v_mfma_f32_16x16x32_f16 v[52:55], v[8:11], v[32:35], 0
	v_cvt_pkrtz_f16_f32 v65, v58, v59
	v_cvt_pkrtz_f16_f32 v64, v56, v57
	v_med3_f32 v76, v68, 0, v79
	v_pk_max_f16 v65, v65, 0
	v_mfma_f32_16x16x32_f16 v[48:51], v[4:7], v[36:39], v[48:51]
	v_pk_max_f16 v64, v64, 0
	v_cvt_u32_f32_e32 v76, v76
	v_cmp_le_i32_e32 vcc, -176, v78
	v_mfma_f32_16x16x32_f16 v[52:55], v[12:15], v[36:39], v[52:55]
	v_lshl_add_u32 v77, v76, 2, v139
	s_and_b64 exec, exec, vcc
	ds_add_u32 v77, v212
	s_mov_b64 exec, -1
	v_mfma_f32_16x16x32_f16 v[72:75], v[80:83], v[64:67], v[84:87]
	ds_read_b128 v[32:35], v122 offset:16384
	ds_read_b128 v[36:39], v123 offset:16384
	s_waitcnt lgkmcnt(3)
	v_mfma_f32_16x16x32_f16 v[56:59], v[0:3], v[40:43], 0
	v_cvt_pkrtz_f16_f32 v67, v54, v55
	v_cvt_pkrtz_f16_f32 v66, v52, v53
	v_pk_max_f16 v67, v67, 0
	v_pk_max_f16 v66, v66, 0
	v_mfma_f32_16x16x32_f16 v[60:63], v[8:11], v[40:43], 0
	v_cvt_pkrtz_f16_f32 v65, v50, v51
	v_cvt_pkrtz_f16_f32 v64, v48, v49
	v_med3_f32 v76, v72, 0, v79
	v_pk_max_f16 v65, v65, 0
	v_mfma_f32_16x16x32_f16 v[56:59], v[4:7], v[44:47], v[56:59]
	v_pk_max_f16 v64, v64, 0
	v_cvt_u32_f32_e32 v76, v76
	v_cmp_le_i32_e32 vcc, -160, v78
	v_mfma_f32_16x16x32_f16 v[60:63], v[12:15], v[44:47], v[60:63]
	v_lshl_add_u32 v77, v76, 2, v139
	s_and_b64 exec, exec, vcc
	ds_add_u32 v77, v212
	s_mov_b64 exec, -1
	v_mfma_f32_16x16x32_f16 v[68:71], v[80:83], v[64:67], v[84:87]
	ds_read_b128 v[40:43], v122 offset:18432
	ds_read_b128 v[44:47], v123 offset:18432
	s_waitcnt lgkmcnt(3)
	v_mfma_f32_16x16x32_f16 v[48:51], v[0:3], v[32:35], 0
	v_cvt_pkrtz_f16_f32 v67, v62, v63
	v_cvt_pkrtz_f16_f32 v66, v60, v61
	v_pk_max_f16 v67, v67, 0
	v_pk_max_f16 v66, v66, 0
	v_mfma_f32_16x16x32_f16 v[52:55], v[8:11], v[32:35], 0
	v_cvt_pkrtz_f16_f32 v65, v58, v59
	v_cvt_pkrtz_f16_f32 v64, v56, v57
	v_med3_f32 v76, v68, 0, v79
	v_pk_max_f16 v65, v65, 0
	v_mfma_f32_16x16x32_f16 v[48:51], v[4:7], v[36:39], v[48:51]
	v_pk_max_f16 v64, v64, 0
	v_cvt_u32_f32_e32 v76, v76
	v_cmp_le_i32_e32 vcc, -144, v78
	v_mfma_f32_16x16x32_f16 v[52:55], v[12:15], v[36:39], v[52:55]
	v_lshl_add_u32 v77, v76, 2, v139
	s_and_b64 exec, exec, vcc
	ds_add_u32 v77, v212
	s_mov_b64 exec, -1
	v_mfma_f32_16x16x32_f16 v[72:75], v[80:83], v[64:67], v[84:87]
	ds_read_b128 v[32:35], v122 offset:20480
	ds_read_b128 v[36:39], v123 offset:20480
	s_waitcnt lgkmcnt(3)
	v_mfma_f32_16x16x32_f16 v[56:59], v[0:3], v[40:43], 0
	v_cvt_pkrtz_f16_f32 v67, v54, v55
	v_cvt_pkrtz_f16_f32 v66, v52, v53
	v_pk_max_f16 v67, v67, 0
	v_pk_max_f16 v66, v66, 0
	v_mfma_f32_16x16x32_f16 v[60:63], v[8:11], v[40:43], 0
	v_cvt_pkrtz_f16_f32 v65, v50, v51
	v_cvt_pkrtz_f16_f32 v64, v48, v49
	v_med3_f32 v76, v72, 0, v79
	v_pk_max_f16 v65, v65, 0
	v_mfma_f32_16x16x32_f16 v[56:59], v[4:7], v[44:47], v[56:59]
	v_pk_max_f16 v64, v64, 0
	v_cvt_u32_f32_e32 v76, v76
	v_cmp_le_i32_e32 vcc, -128, v78
	v_mfma_f32_16x16x32_f16 v[60:63], v[12:15], v[44:47], v[60:63]
	v_lshl_add_u32 v77, v76, 2, v139
	s_and_b64 exec, exec, vcc
	ds_add_u32 v77, v212
	s_mov_b64 exec, -1
	v_mfma_f32_16x16x32_f16 v[68:71], v[80:83], v[64:67], v[84:87]
	ds_read_b128 v[40:43], v122 offset:22528
	ds_read_b128 v[44:47], v123 offset:22528
	s_waitcnt lgkmcnt(3)
	v_mfma_f32_16x16x32_f16 v[48:51], v[0:3], v[32:35], 0
	v_cvt_pkrtz_f16_f32 v67, v62, v63
	v_cvt_pkrtz_f16_f32 v66, v60, v61
	v_pk_max_f16 v67, v67, 0
	v_pk_max_f16 v66, v66, 0
	v_mfma_f32_16x16x32_f16 v[52:55], v[8:11], v[32:35], 0
	v_cvt_pkrtz_f16_f32 v65, v58, v59
	v_cvt_pkrtz_f16_f32 v64, v56, v57
	v_med3_f32 v76, v68, 0, v79
	v_pk_max_f16 v65, v65, 0
	v_mfma_f32_16x16x32_f16 v[48:51], v[4:7], v[36:39], v[48:51]
	v_pk_max_f16 v64, v64, 0
	v_cvt_u32_f32_e32 v76, v76
	v_cmp_le_i32_e32 vcc, -112, v78
	v_mfma_f32_16x16x32_f16 v[52:55], v[12:15], v[36:39], v[52:55]
	v_lshl_add_u32 v77, v76, 2, v139
	s_and_b64 exec, exec, vcc
	ds_add_u32 v77, v212
	s_mov_b64 exec, -1
	v_mfma_f32_16x16x32_f16 v[72:75], v[80:83], v[64:67], v[84:87]
	ds_read_b128 v[32:35], v122 offset:24576
	ds_read_b128 v[36:39], v123 offset:24576
	s_waitcnt lgkmcnt(3)
	v_mfma_f32_16x16x32_f16 v[56:59], v[0:3], v[40:43], 0
	v_cvt_pkrtz_f16_f32 v67, v54, v55
	v_cvt_pkrtz_f16_f32 v66, v52, v53
	v_pk_max_f16 v67, v67, 0
	v_pk_max_f16 v66, v66, 0
	v_mfma_f32_16x16x32_f16 v[60:63], v[8:11], v[40:43], 0
	v_cvt_pkrtz_f16_f32 v65, v50, v51
	v_cvt_pkrtz_f16_f32 v64, v48, v49
	v_med3_f32 v76, v72, 0, v79
	v_pk_max_f16 v65, v65, 0
	v_mfma_f32_16x16x32_f16 v[56:59], v[4:7], v[44:47], v[56:59]
	v_pk_max_f16 v64, v64, 0
	v_cvt_u32_f32_e32 v76, v76
	v_cmp_le_i32_e32 vcc, -96, v78
	v_mfma_f32_16x16x32_f16 v[60:63], v[12:15], v[44:47], v[60:63]
	v_lshl_add_u32 v77, v76, 2, v139
	s_and_b64 exec, exec, vcc
	ds_add_u32 v77, v212
	s_mov_b64 exec, -1
	v_mfma_f32_16x16x32_f16 v[68:71], v[80:83], v[64:67], v[84:87]
	ds_read_b128 v[40:43], v122 offset:26624
	ds_read_b128 v[44:47], v123 offset:26624
	s_waitcnt lgkmcnt(3)
	v_mfma_f32_16x16x32_f16 v[48:51], v[0:3], v[32:35], 0
	v_cvt_pkrtz_f16_f32 v67, v62, v63
	v_cvt_pkrtz_f16_f32 v66, v60, v61
	v_pk_max_f16 v67, v67, 0
	v_pk_max_f16 v66, v66, 0
	v_mfma_f32_16x16x32_f16 v[52:55], v[8:11], v[32:35], 0
	v_cvt_pkrtz_f16_f32 v65, v58, v59
	v_cvt_pkrtz_f16_f32 v64, v56, v57
	v_med3_f32 v76, v68, 0, v79
	v_pk_max_f16 v65, v65, 0
	v_mfma_f32_16x16x32_f16 v[48:51], v[4:7], v[36:39], v[48:51]
	v_pk_max_f16 v64, v64, 0
	v_cvt_u32_f32_e32 v76, v76
	v_cmp_le_i32_e32 vcc, -80, v78
	v_mfma_f32_16x16x32_f16 v[52:55], v[12:15], v[36:39], v[52:55]
	v_lshl_add_u32 v77, v76, 2, v139
	s_and_b64 exec, exec, vcc
	ds_add_u32 v77, v212
	s_mov_b64 exec, -1
	v_mfma_f32_16x16x32_f16 v[72:75], v[80:83], v[64:67], v[84:87]
	ds_read_b128 v[32:35], v122 offset:28672
	ds_read_b128 v[36:39], v123 offset:28672
	s_waitcnt lgkmcnt(3)
; template <int PASS> ...
;     ...
;         for (int e = 0; e < 8; ++e) { const unsigned char* tp = lp + (hb * 8 + e) * 2048; kf[e][0] = *(const h16x8*)(tp + ((fq ^ sw) << 4)); kf[e][1] = *(const h16x8*)(tp + (((fq + 4) ^ sw) << 4)); }
; #pragma unroll
;         for (int e = 0; e < 8; ++e) { const int T = Tbase + hb * 8 + e;
;             f32x4 a0 = (f32x4){0.f, 0.f, 0.f, 0.f}, a1 = a0;
;             a0 = __builtin_amdgcn_mfma_f32_16x16x32_f16(aq[0][0], kf[e][0], a0, 0, 0, 0); a0 = __builtin_amdgcn_mfma_f32_16x16x32_f16(aq[0][1], kf[e][1], a0, 0, 0, 0);
;             a1 = __builtin_amdgcn_mfma_f32_16x16x32_f16(aq[1][0], kf[e][0], a1, 0, 0, 0); a1 = __builtin_amdgcn_mfma_f32_16x16x32_f16(aq[1][1], kf[e][1], a1, 0, 0, 0);
;             const h16x2 z2 = (h16x2){(h16)0.f, (h16)0.f};
;             const h16x2 r0 = __builtin_elementwise_max(__builtin_bit_cast(h16x2, __builtin_amdgcn_cvt_pkrtz(a0[0], a0[1])), z2), r1 = __builtin_elementwise_max(__builtin_bit_cast(h16x2, __builtin_amdgcn_cvt_pkrtz(a0[2], a0[3])), z2);
;             const h16x2 r2 = __builtin_elementwise_max(__builtin_bit_cast(h16x2, __builtin_amdgcn_cvt_pkrtz(a1[0], a1[1])), z2), r3 = __builtin_elementwise_max(__builtin_bit_cast(h16x2, __builtin_amdgcn_cvt_pkrtz(a1[2], a1[3])), z2);
;             const float sa = __builtin_amdgcn_fdot2(r0, wp[0], __builtin_amdgcn_fdot2(r1, wp[1], __builtin_amdgcn_fdot2(r2, wp[2], __builtin_amdgcn_fdot2(r3, wp[3], 0.f, false), false), false), false);
;             const int key = 16 * T + fr;
;             if (key <= tq) {
;                 const unsigned bin = (unsigned)(int)fminf(fmaxf(sa * 32.f + 128.f, 0.f), 255.f);
;                 if (PASS == 1) { if (bin >= b0) atomicAdd(&myhist[fq * 256 + bin], 1u); }
; __device__ __forceinline__ void dsa_select(const h16* PROJ, unsigned short* IDX, int* CNT, unsigned char* shm, unsigned* bar, unsigned xcc, unsigned xrank) {
;     ...
;             float wv[8];
;             { const h16x8 w8 = *(const h16x8*)(PROJ + O_WI + (size_t)(tokbase + tq) * 8);
; #pragma unroll
;               for (int h = 0; h < 8; ++h) wv[h] = (float)w8[h] * 0.04419417382415922f; }
;             h16x2 wp[4];
; #pragma unroll
;             for (int h = 0; h < 4; ++h) { wp[h].x = (h16)wv[(h >> 1) * 4 + (h & 1) * 2]; wp[h].y = (h16)wv[(h >> 1) * 4 + (h & 1) * 2 + 1]; }
	v_mfma_f32_16x16x32_f16 v[56:59], v[0:3], v[40:43], 0
	v_cvt_pkrtz_f16_f32 v67, v54, v55
	v_cvt_pkrtz_f16_f32 v66, v52, v53
	v_pk_max_f16 v67, v67, 0
	v_pk_max_f16 v66, v66, 0
	v_mfma_f32_16x16x32_f16 v[60:63], v[8:11], v[40:43], 0
	v_cvt_pkrtz_f16_f32 v65, v50, v51
	v_cvt_pkrtz_f16_f32 v64, v48, v49
	v_med3_f32 v76, v72, 0, v79
	v_pk_max_f16 v65, v65, 0
	v_mfma_f32_16x16x32_f16 v[56:59], v[4:7], v[44:47], v[56:59]
	v_pk_max_f16 v64, v64, 0
	v_cvt_u32_f32_e32 v76, v76
	v_cmp_le_i32_e32 vcc, -64, v78
	v_mfma_f32_16x16x32_f16 v[60:63], v[12:15], v[44:47], v[60:63]
	v_lshl_add_u32 v77, v76, 2, v139
	s_and_b64 exec, exec, vcc
	ds_add_u32 v77, v212
	s_mov_b64 exec, -1
	v_mfma_f32_16x16x32_f16 v[68:71], v[80:83], v[64:67], v[84:87]
	ds_read_b128 v[40:43], v122 offset:30720
	ds_read_b128 v[44:47], v123 offset:30720
	s_waitcnt lgkmcnt(3)
	v_mfma_f32_16x16x32_f16 v[48:51], v[0:3], v[32:35], 0
	v_cvt_pkrtz_f16_f32 v67, v62, v63
	v_cvt_pkrtz_f16_f32 v66, v60, v61
	v_pk_max_f16 v67, v67, 0
	v_pk_max_f16 v66, v66, 0
	v_mfma_f32_16x16x32_f16 v[52:55], v[8:11], v[32:35], 0
	v_cvt_pkrtz_f16_f32 v65, v58, v59
	v_cvt_pkrtz_f16_f32 v64, v56, v57
	v_med3_f32 v76, v68, 0, v79
	v_pk_max_f16 v65, v65, 0
	v_mfma_f32_16x16x32_f16 v[48:51], v[4:7], v[36:39], v[48:51]
	v_pk_max_f16 v64, v64, 0
	v_cvt_u32_f32_e32 v76, v76
	v_cmp_le_i32_e32 vcc, -48, v78
	v_mfma_f32_16x16x32_f16 v[52:55], v[12:15], v[36:39], v[52:55]
	v_lshl_add_u32 v77, v76, 2, v139
	s_and_b64 exec, exec, vcc
	ds_add_u32 v77, v212
	s_mov_b64 exec, -1
	v_mfma_f32_16x16x32_f16 v[72:75], v[80:83], v[64:67], v[84:87]
	s_nop 3
	s_waitcnt lgkmcnt(1)
	v_mfma_f32_16x16x32_f16 v[56:59], v[0:3], v[40:43], 0
	v_cvt_pkrtz_f16_f32 v67, v54, v55
	v_cvt_pkrtz_f16_f32 v66, v52, v53
	v_pk_max_f16 v67, v67, 0
	v_pk_max_f16 v66, v66, 0
	v_mfma_f32_16x16x32_f16 v[60:63], v[8:11], v[40:43], 0
	v_cvt_pkrtz_f16_f32 v65, v50, v51
	v_cvt_pkrtz_f16_f32 v64, v48, v49
	v_med3_f32 v76, v72, 0, v79
	v_pk_max_f16 v65, v65, 0
	v_mfma_f32_16x16x32_f16 v[56:59], v[4:7], v[44:47], v[56:59]
	v_pk_max_f16 v64, v64, 0
	v_cvt_u32_f32_e32 v76, v76
	v_cmp_le_i32_e32 vcc, -32, v78
	v_mfma_f32_16x16x32_f16 v[60:63], v[12:15], v[44:47], v[60:63]
	v_lshl_add_u32 v77, v76, 2, v139
	s_and_b64 exec, exec, vcc
	ds_add_u32 v77, v212
	s_mov_b64 exec, -1
	v_mfma_f32_16x16x32_f16 v[68:71], v[80:83], v[64:67], v[84:87]
	s_nop 3
	v_cvt_pkrtz_f16_f32 v67, v62, v63
	v_cvt_pkrtz_f16_f32 v66, v60, v61
	v_pk_max_f16 v67, v67, 0
	v_pk_max_f16 v66, v66, 0
	v_cvt_pkrtz_f16_f32 v65, v58, v59
	v_cvt_pkrtz_f16_f32 v64, v56, v57
	v_med3_f32 v76, v68, 0, v79
	v_pk_max_f16 v65, v65, 0
	v_pk_max_f16 v64, v64, 0
	v_cvt_u32_f32_e32 v76, v76
	v_cmp_le_i32_e32 vcc, -16, v78
	v_lshl_add_u32 v77, v76, 2, v139
	s_and_b64 exec, exec, vcc
	ds_add_u32 v77, v212
	s_mov_b64 exec, -1
	v_mfma_f32_16x16x32_f16 v[72:75], v[80:83], v[64:67], v[84:87]
	s_nop 7
	s_nop 3
	v_med3_f32 v76, v72, 0, v79
	v_cvt_u32_f32_e32 v76, v76
	v_cmp_le_i32_e32 vcc, 0, v78
	v_lshl_add_u32 v77, v76, 2, v139
	s_and_b64 exec, exec, vcc
	ds_add_u32 v77, v212
	s_mov_b64 exec, -1
	s_setprio 0
	s_branch .LBB0_239
.Lp1_interior:
	ds_read_b128 v[32:35], v122
	ds_read_b128 v[36:39], v123
	ds_read_b128 v[40:43], v122 offset:2048
	ds_read_b128 v[44:47], v123 offset:2048
	v_mov_b32_e32 v79, 0x437f0000
	v_mul_f32_e32 v88, v106, v106
	v_fmac_f32_e32 v88, v107, v107
	v_fmac_f32_e32 v88, v108, v108
	v_fmac_f32_e32 v88, v109, v109
	v_fmac_f32_e32 v88, v110, v110
	v_fmac_f32_e32 v88, v111, v111
	v_fmac_f32_e32 v88, v112, v112
	v_fmac_f32_e32 v88, v113, v113
	v_max_f32_e32 v88, 0x358637bd, v88
	v_rsq_f32_e32 v88, v88
	s_mov_b32 s62, 0x100001
	s_mov_b32 s63, 0x10000100
	v_mul_f32_e32 v88, 4.0, v88
	v_cvt_pkrtz_f16_f32 v88, v88, v88
	v_pk_mul_f16 v80, v193, v88
	v_pk_mul_f16 v81, v194, v88
	v_pk_mul_f16 v82, v195, v88
	v_pk_mul_f16 v83, v196, v88
	v_cndmask_b32_e64 v80, 0, v80, s[62:63]
	v_cndmask_b32_e64 v81, 0, v81, s[62:63]
	v_cndmask_b32_e64 v82, 0, v82, s[62:63]
	v_cndmask_b32_e64 v83, 0, v83, s[62:63]
	v_mov_b32_e32 v84, 0x43000000
	v_mov_b32_e32 v85, 0
	v_mov_b32_e32 v86, 0
	v_mov_b32_e32 v87, 0
	s_waitcnt lgkmcnt(2)
	v_mfma_f32_16x16x32_f16 v[48:51], v[0:3], v[32:35], 0
	v_mfma_f32_16x16x32_f16 v[52:55], v[8:11], v[32:35], 0
	v_mfma_f32_16x16x32_f16 v[48:51], v[4:7], v[36:39], v[48:51]
	v_mfma_f32_16x16x32_f16 v[52:55], v[12:15], v[36:39], v[52:55]
	s_nop 3
	ds_read_b128 v[32:35], v122 offset:4096
	ds_read_b128 v[36:39], v123 offset:4096
	s_waitcnt lgkmcnt(2)
	v_mfma_f32_16x16x32_f16 v[56:59], v[0:3], v[40:43], 0
	v_cvt_pkrtz_f16_f32 v67, v54, v55
	v_cvt_pkrtz_f16_f32 v66, v52, v53
	v_pk_max_f16 v67, v67, 0
	v_pk_max_f16 v66, v66, 0
	v_mfma_f32_16x16x32_f16 v[60:63], v[8:11], v[40:43], 0
	v_cvt_pkrtz_f16_f32 v65, v50, v51
	v_cvt_pkrtz_f16_f32 v64, v48, v49
	v_pk_max_f16 v65, v65, 0
	v_mfma_f32_16x16x32_f16 v[56:59], v[4:7], v[44:47], v[56:59]
	v_pk_max_f16 v64, v64, 0
	v_mfma_f32_16x16x32_f16 v[60:63], v[12:15], v[44:47], v[60:63]
	s_nop 3
	v_mfma_f32_16x16x32_f16 v[68:71], v[80:83], v[64:67], v[84:87]
	ds_read_b128 v[40:43], v122 offset:6144
	ds_read_b128 v[44:47], v123 offset:6144
	s_waitcnt lgkmcnt(2)
	v_mfma_f32_16x16x32_f16 v[48:51], v[0:3], v[32:35], 0
	v_cvt_pkrtz_f16_f32 v67, v62, v63
	v_cvt_pkrtz_f16_f32 v66, v60, v61
	v_pk_max_f16 v67, v67, 0
	v_pk_max_f16 v66, v66, 0
	v_mfma_f32_16x16x32_f16 v[52:55], v[8:11], v[32:35], 0
	v_cvt_pkrtz_f16_f32 v65, v58, v59
	v_cvt_pkrtz_f16_f32 v64, v56, v57
	v_med3_f32 v76, v68, 0, v79
	v_pk_max_f16 v65, v65, 0
	v_mfma_f32_16x16x32_f16 v[48:51], v[4:7], v[36:39], v[48:51]
	v_pk_max_f16 v64, v64, 0
	v_cvt_u32_f32_e32 v76, v76
	v_mfma_f32_16x16x32_f16 v[52:55], v[12:15], v[36:39], v[52:55]
	v_lshl_add_u32 v77, v76, 2, v139
	s_nop 0
	ds_add_u32 v77, v212
	s_nop 0
	s_nop 0
	v_mfma_f32_16x16x32_f16 v[72:75], v[80:83], v[64:67], v[84:87]
	ds_read_b128 v[32:35], v122 offset:8192
	ds_read_b128 v[36:39], v123 offset:8192
	s_waitcnt lgkmcnt(3)
; template <int PASS> ...
;     ...
;         for (int e = 0; e < 8; ++e) { const unsigned char* tp = lp + (hb * 8 + e) * 2048; kf[e][0] = *(const h16x8*)(tp + ((fq ^ sw) << 4)); kf[e][1] = *(const h16x8*)(tp + (((fq + 4) ^ sw) << 4)); }
; #pragma unroll
;         for (int e = 0; e < 8; ++e) { const int T = Tbase + hb * 8 + e;
;             f32x4 a0 = (f32x4){0.f, 0.f, 0.f, 0.f}, a1 = a0;
;             a0 = __builtin_amdgcn_mfma_f32_16x16x32_f16(aq[0][0], kf[e][0], a0, 0, 0, 0); a0 = __builtin_amdgcn_mfma_f32_16x16x32_f16(aq[0][1], kf[e][1], a0, 0, 0, 0);
;             a1 = __builtin_amdgcn_mfma_f32_16x16x32_f16(aq[1][0], kf[e][0], a1, 0, 0, 0); a1 = __builtin_amdgcn_mfma_f32_16x16x32_f16(aq[1][1], kf[e][1], a1, 0, 0, 0);
;             const h16x2 z2 = (h16x2){(h16)0.f, (h16)0.f};
;             const h16x2 r0 = __builtin_elementwise_max(__builtin_bit_cast(h16x2, __builtin_amdgcn_cvt_pkrtz(a0[0], a0[1])), z2), r1 = __builtin_elementwise_max(__builtin_bit_cast(h16x2, __builtin_amdgcn_cvt_pkrtz(a0[2], a0[3])), z2);
;             const h16x2 r2 = __builtin_elementwise_max(__builtin_bit_cast(h16x2, __builtin_amdgcn_cvt_pkrtz(a1[0], a1[1])), z2), r3 = __builtin_elementwise_max(__builtin_bit_cast(h16x2, __builtin_amdgcn_cvt_pkrtz(a1[2], a1[3])), z2);
;             const float sa = __builtin_amdgcn_fdot2(r0, wp[0], __builtin_amdgcn_fdot2(r1, wp[1], __builtin_amdgcn_fdot2(r2, wp[2], __builtin_amdgcn_fdot2(r3, wp[3], 0.f, false), false), false), false);
;             const int key = 16 * T + fr;
;             if (key <= tq) {
;                 const unsigned bin = (unsigned)(int)fminf(fmaxf(sa * 32.f + 128.f, 0.f), 255.f);
;                 if (PASS == 1) { if (bin >= b0) atomicAdd(&myhist[fq * 256 + bin], 1u); }
	v_mfma_f32_16x16x32_f16 v[56:59], v[0:3], v[40:43], 0
	v_cvt_pkrtz_f16_f32 v67, v54, v55
	v_cvt_pkrtz_f16_f32 v66, v52, v53
	v_pk_max_f16 v67, v67, 0
	v_pk_max_f16 v66, v66, 0
	v_mfma_f32_16x16x32_f16 v[60:63], v[8:11], v[40:43], 0
	v_cvt_pkrtz_f16_f32 v65, v50, v51
	v_cvt_pkrtz_f16_f32 v64, v48, v49
	v_med3_f32 v76, v72, 0, v79
	v_pk_max_f16 v65, v65, 0
	v_mfma_f32_16x16x32_f16 v[56:59], v[4:7], v[44:47], v[56:59]
	v_pk_max_f16 v64, v64, 0
	v_cvt_u32_f32_e32 v76, v76
	v_mfma_f32_16x16x32_f16 v[60:63], v[12:15], v[44:47], v[60:63]
	v_lshl_add_u32 v77, v76, 2, v139
	s_nop 0
	ds_add_u32 v77, v212
	s_nop 0
	s_nop 0
	v_mfma_f32_16x16x32_f16 v[68:71], v[80:83], v[64:67], v[84:87]
	ds_read_b128 v[40:43], v122 offset:10240
	ds_read_b128 v[44:47], v123 offset:10240
	s_waitcnt lgkmcnt(3)
	v_mfma_f32_16x16x32_f16 v[48:51], v[0:3], v[32:35], 0
	v_cvt_pkrtz_f16_f32 v67, v62, v63
	v_cvt_pkrtz_f16_f32 v66, v60, v61
	v_pk_max_f16 v67, v67, 0
	v_pk_max_f16 v66, v66, 0
	v_mfma_f32_16x16x32_f16 v[52:55], v[8:11], v[32:35], 0
	v_cvt_pkrtz_f16_f32 v65, v58, v59
	v_cvt_pkrtz_f16_f32 v64, v56, v57
	v_med3_f32 v76, v68, 0, v79
	v_pk_max_f16 v65, v65, 0
	v_mfma_f32_16x16x32_f16 v[48:51], v[4:7], v[36:39], v[48:51]
	v_pk_max_f16 v64, v64, 0
	v_cvt_u32_f32_e32 v76, v76
	v_mfma_f32_16x16x32_f16 v[52:55], v[12:15], v[36:39], v[52:55]
	v_lshl_add_u32 v77, v76, 2, v139
	s_nop 0
	ds_add_u32 v77, v212
	s_nop 0
	s_nop 0
	v_mfma_f32_16x16x32_f16 v[72:75], v[80:83], v[64:67], v[84:87]
	ds_read_b128 v[32:35], v122 offset:12288
	ds_read_b128 v[36:39], v123 offset:12288
	s_waitcnt lgkmcnt(3)
	v_mfma_f32_16x16x32_f16 v[56:59], v[0:3], v[40:43], 0
	v_cvt_pkrtz_f16_f32 v67, v54, v55
	v_cvt_pkrtz_f16_f32 v66, v52, v53
	v_pk_max_f16 v67, v67, 0
	v_pk_max_f16 v66, v66, 0
	v_mfma_f32_16x16x32_f16 v[60:63], v[8:11], v[40:43], 0
	v_cvt_pkrtz_f16_f32 v65, v50, v51
	v_cvt_pkrtz_f16_f32 v64, v48, v49
	v_med3_f32 v76, v72, 0, v79
	v_pk_max_f16 v65, v65, 0
	v_mfma_f32_16x16x32_f16 v[56:59], v[4:7], v[44:47], v[56:59]
	v_pk_max_f16 v64, v64, 0
	v_cvt_u32_f32_e32 v76, v76
	v_mfma_f32_16x16x32_f16 v[60:63], v[12:15], v[44:47], v[60:63]
	v_lshl_add_u32 v77, v76, 2, v139
	s_nop 0
	ds_add_u32 v77, v212
	s_nop 0
	s_nop 0
	v_mfma_f32_16x16x32_f16 v[68:71], v[80:83], v[64:67], v[84:87]
	ds_read_b128 v[40:43], v122 offset:14336
	ds_read_b128 v[44:47], v123 offset:14336
	s_waitcnt lgkmcnt(3)
	v_mfma_f32_16x16x32_f16 v[48:51], v[0:3], v[32:35], 0
	v_cvt_pkrtz_f16_f32 v67, v62, v63
	v_cvt_pkrtz_f16_f32 v66, v60, v61
	v_pk_max_f16 v67, v67, 0
	v_pk_max_f16 v66, v66, 0
	v_mfma_f32_16x16x32_f16 v[52:55], v[8:11], v[32:35], 0
	v_cvt_pkrtz_f16_f32 v65, v58, v59
	v_cvt_pkrtz_f16_f32 v64, v56, v57
	v_med3_f32 v76, v68, 0, v79
	v_pk_max_f16 v65, v65, 0
	v_mfma_f32_16x16x32_f16 v[48:51], v[4:7], v[36:39], v[48:51]
	v_pk_max_f16 v64, v64, 0
	v_cvt_u32_f32_e32 v76, v76
	v_mfma_f32_16x16x32_f16 v[52:55], v[12:15], v[36:39], v[52:55]
	v_lshl_add_u32 v77, v76, 2, v139
	s_nop 0
	ds_add_u32 v77, v212
	s_nop 0
	s_nop 0
	v_mfma_f32_16x16x32_f16 v[72:75], v[80:83], v[64:67], v[84:87]
	ds_read_b128 v[32:35], v122 offset:16384
	ds_read_b128 v[36:39], v123 offset:16384
	s_waitcnt lgkmcnt(3)
	v_mfma_f32_16x16x32_f16 v[56:59], v[0:3], v[40:43], 0
	v_cvt_pkrtz_f16_f32 v67, v54, v55
	v_cvt_pkrtz_f16_f32 v66, v52, v53
	v_pk_max_f16 v67, v67, 0
	v_pk_max_f16 v66, v66, 0
	v_mfma_f32_16x16x32_f16 v[60:63], v[8:11], v[40:43], 0
	v_cvt_pkrtz_f16_f32 v65, v50, v51
	v_cvt_pkrtz_f16_f32 v64, v48, v49
	v_med3_f32 v76, v72, 0, v79
	v_pk_max_f16 v65, v65, 0
	v_mfma_f32_16x16x32_f16 v[56:59], v[4:7], v[44:47], v[56:59]
	v_pk_max_f16 v64, v64, 0
	v_cvt_u32_f32_e32 v76, v76
	v_mfma_f32_16x16x32_f16 v[60:63], v[12:15], v[44:47], v[60:63]
	v_lshl_add_u32 v77, v76, 2, v139
	s_nop 0
	ds_add_u32 v77, v212
	s_nop 0
	s_nop 0
	v_mfma_f32_16x16x32_f16 v[68:71], v[80:83], v[64:67], v[84:87]
	ds_read_b128 v[40:43], v122 offset:18432
	ds_read_b128 v[44:47], v123 offset:18432
	s_waitcnt lgkmcnt(3)
	v_mfma_f32_16x16x32_f16 v[48:51], v[0:3], v[32:35], 0
	v_cvt_pkrtz_f16_f32 v67, v62, v63
	v_cvt_pkrtz_f16_f32 v66, v60, v61
	v_pk_max_f16 v67, v67, 0
	v_pk_max_f16 v66, v66, 0
	v_mfma_f32_16x16x32_f16 v[52:55], v[8:11], v[32:35], 0
	v_cvt_pkrtz_f16_f32 v65, v58, v59
	v_cvt_pkrtz_f16_f32 v64, v56, v57
	v_med3_f32 v76, v68, 0, v79
	v_pk_max_f16 v65, v65, 0
	v_mfma_f32_16x16x32_f16 v[48:51], v[4:7], v[36:39], v[48:51]
	v_pk_max_f16 v64, v64, 0
	v_cvt_u32_f32_e32 v76, v76
	v_mfma_f32_16x16x32_f16 v[52:55], v[12:15], v[36:39], v[52:55]
	v_lshl_add_u32 v77, v76, 2, v139
	s_nop 0
	ds_add_u32 v77, v212
	s_nop 0
	s_nop 0
	v_mfma_f32_16x16x32_f16 v[72:75], v[80:83], v[64:67], v[84:87]
	ds_read_b128 v[32:35], v122 offset:20480
	ds_read_b128 v[36:39], v123 offset:20480
	s_waitcnt lgkmcnt(3)
	v_mfma_f32_16x16x32_f16 v[56:59], v[0:3], v[40:43], 0
	v_cvt_pkrtz_f16_f32 v67, v54, v55
	v_cvt_pkrtz_f16_f32 v66, v52, v53
	v_pk_max_f16 v67, v67, 0
	v_pk_max_f16 v66, v66, 0
	v_mfma_f32_16x16x32_f16 v[60:63], v[8:11], v[40:43], 0
	v_cvt_pkrtz_f16_f32 v65, v50, v51
	v_cvt_pkrtz_f16_f32 v64, v48, v49
	v_med3_f32 v76, v72, 0, v79
	v_pk_max_f16 v65, v65, 0
	v_mfma_f32_16x16x32_f16 v[56:59], v[4:7], v[44:47], v[56:59]
	v_pk_max_f16 v64, v64, 0
	v_cvt_u32_f32_e32 v76, v76
	v_mfma_f32_16x16x32_f16 v[60:63], v[12:15], v[44:47], v[60:63]
	v_lshl_add_u32 v77, v76, 2, v139
	s_nop 0
	ds_add_u32 v77, v212
	s_nop 0
	s_nop 0
	v_mfma_f32_16x16x32_f16 v[68:71], v[80:83], v[64:67], v[84:87]
	ds_read_b128 v[40:43], v122 offset:22528
	ds_read_b128 v[44:47], v123 offset:22528
	s_waitcnt lgkmcnt(3)
; template <int PASS> ...
;     ...
;         for (int e = 0; e < 8; ++e) { const unsigned char* tp = lp + (hb * 8 + e) * 2048; kf[e][0] = *(const h16x8*)(tp + ((fq ^ sw) << 4)); kf[e][1] = *(const h16x8*)(tp + (((fq + 4) ^ sw) << 4)); }
; #pragma unroll
;         for (int e = 0; e < 8; ++e) { const int T = Tbase + hb * 8 + e;
;             f32x4 a0 = (f32x4){0.f, 0.f, 0.f, 0.f}, a1 = a0;
;             a0 = __builtin_amdgcn_mfma_f32_16x16x32_f16(aq[0][0], kf[e][0], a0, 0, 0, 0); a0 = __builtin_amdgcn_mfma_f32_16x16x32_f16(aq[0][1], kf[e][1], a0, 0, 0, 0);
;             a1 = __builtin_amdgcn_mfma_f32_16x16x32_f16(aq[1][0], kf[e][0], a1, 0, 0, 0); a1 = __builtin_amdgcn_mfma_f32_16x16x32_f16(aq[1][1], kf[e][1], a1, 0, 0, 0);
;             const h16x2 z2 = (h16x2){(h16)0.f, (h16)0.f};
;             const h16x2 r0 = __builtin_elementwise_max(__builtin_bit_cast(h16x2, __builtin_amdgcn_cvt_pkrtz(a0[0], a0[1])), z2), r1 = __builtin_elementwise_max(__builtin_bit_cast(h16x2, __builtin_amdgcn_cvt_pkrtz(a0[2], a0[3])), z2);
;             const h16x2 r2 = __builtin_elementwise_max(__builtin_bit_cast(h16x2, __builtin_amdgcn_cvt_pkrtz(a1[0], a1[1])), z2), r3 = __builtin_elementwise_max(__builtin_bit_cast(h16x2, __builtin_amdgcn_cvt_pkrtz(a1[2], a1[3])), z2);
;             const float sa = __builtin_amdgcn_fdot2(r0, wp[0], __builtin_amdgcn_fdot2(r1, wp[1], __builtin_amdgcn_fdot2(r2, wp[2], __builtin_amdgcn_fdot2(r3, wp[3], 0.f, false), false), false), false);
;             const int key = 16 * T + fr;
;             if (key <= tq) {
;                 const unsigned bin = (unsigned)(int)fminf(fmaxf(sa * 32.f + 128.f, 0.f), 255.f);
;                 if (PASS == 1) { if (bin >= b0) atomicAdd(&myhist[fq * 256 + bin], 1u); }
	v_mfma_f32_16x16x32_f16 v[48:51], v[0:3], v[32:35], 0
	v_cvt_pkrtz_f16_f32 v67, v62, v63
	v_cvt_pkrtz_f16_f32 v66, v60, v61
	v_pk_max_f16 v67, v67, 0
	v_pk_max_f16 v66, v66, 0
	v_mfma_f32_16x16x32_f16 v[52:55], v[8:11], v[32:35], 0
	v_cvt_pkrtz_f16_f32 v65, v58, v59
	v_cvt_pkrtz_f16_f32 v64, v56, v57
	v_med3_f32 v76, v68, 0, v79
	v_pk_max_f16 v65, v65, 0
	v_mfma_f32_16x16x32_f16 v[48:51], v[4:7], v[36:39], v[48:51]
	v_pk_max_f16 v64, v64, 0
	v_cvt_u32_f32_e32 v76, v76
	v_mfma_f32_16x16x32_f16 v[52:55], v[12:15], v[36:39], v[52:55]
	v_lshl_add_u32 v77, v76, 2, v139
	s_nop 0
	ds_add_u32 v77, v212
	s_nop 0
	s_nop 0
	v_mfma_f32_16x16x32_f16 v[72:75], v[80:83], v[64:67], v[84:87]
	ds_read_b128 v[32:35], v122 offset:24576
	ds_read_b128 v[36:39], v123 offset:24576
	s_waitcnt lgkmcnt(3)
	v_mfma_f32_16x16x32_f16 v[56:59], v[0:3], v[40:43], 0
	v_cvt_pkrtz_f16_f32 v67, v54, v55
	v_cvt_pkrtz_f16_f32 v66, v52, v53
	v_pk_max_f16 v67, v67, 0
	v_pk_max_f16 v66, v66, 0
	v_mfma_f32_16x16x32_f16 v[60:63], v[8:11], v[40:43], 0
	v_cvt_pkrtz_f16_f32 v65, v50, v51
	v_cvt_pkrtz_f16_f32 v64, v48, v49
	v_med3_f32 v76, v72, 0, v79
	v_pk_max_f16 v65, v65, 0
	v_mfma_f32_16x16x32_f16 v[56:59], v[4:7], v[44:47], v[56:59]
	v_pk_max_f16 v64, v64, 0
	v_cvt_u32_f32_e32 v76, v76
	v_mfma_f32_16x16x32_f16 v[60:63], v[12:15], v[44:47], v[60:63]
	v_lshl_add_u32 v77, v76, 2, v139
	s_nop 0
	ds_add_u32 v77, v212
	s_nop 0
	s_nop 0
	v_mfma_f32_16x16x32_f16 v[68:71], v[80:83], v[64:67], v[84:87]
	ds_read_b128 v[40:43], v122 offset:26624
	ds_read_b128 v[44:47], v123 offset:26624
	s_waitcnt lgkmcnt(3)
	v_mfma_f32_16x16x32_f16 v[48:51], v[0:3], v[32:35], 0
	v_cvt_pkrtz_f16_f32 v67, v62, v63
	v_cvt_pkrtz_f16_f32 v66, v60, v61
	v_pk_max_f16 v67, v67, 0
	v_pk_max_f16 v66, v66, 0
	v_mfma_f32_16x16x32_f16 v[52:55], v[8:11], v[32:35], 0
	v_cvt_pkrtz_f16_f32 v65, v58, v59
	v_cvt_pkrtz_f16_f32 v64, v56, v57
	v_med3_f32 v76, v68, 0, v79
	v_pk_max_f16 v65, v65, 0
	v_mfma_f32_16x16x32_f16 v[48:51], v[4:7], v[36:39], v[48:51]
	v_pk_max_f16 v64, v64, 0
	v_cvt_u32_f32_e32 v76, v76
	v_mfma_f32_16x16x32_f16 v[52:55], v[12:15], v[36:39], v[52:55]
	v_lshl_add_u32 v77, v76, 2, v139
	s_nop 0
	ds_add_u32 v77, v212
	s_nop 0
	s_nop 0
	v_mfma_f32_16x16x32_f16 v[72:75], v[80:83], v[64:67], v[84:87]
	ds_read_b128 v[32:35], v122 offset:28672
	ds_read_b128 v[36:39], v123 offset:28672
	s_waitcnt lgkmcnt(3)
	v_mfma_f32_16x16x32_f16 v[56:59], v[0:3], v[40:43], 0
	v_cvt_pkrtz_f16_f32 v67, v54, v55
	v_cvt_pkrtz_f16_f32 v66, v52, v53
	v_pk_max_f16 v67, v67, 0
	v_pk_max_f16 v66, v66, 0
	v_mfma_f32_16x16x32_f16 v[60:63], v[8:11], v[40:43], 0
	v_cvt_pkrtz_f16_f32 v65, v50, v51
	v_cvt_pkrtz_f16_f32 v64, v48, v49
	v_med3_f32 v76, v72, 0, v79
	v_pk_max_f16 v65, v65, 0
	v_mfma_f32_16x16x32_f16 v[56:59], v[4:7], v[44:47], v[56:59]
	v_pk_max_f16 v64, v64, 0
	v_cvt_u32_f32_e32 v76, v76
	v_mfma_f32_16x16x32_f16 v[60:63], v[12:15], v[44:47], v[60:63]
	v_lshl_add_u32 v77, v76, 2, v139
	s_nop 0
	ds_add_u32 v77, v212
	s_nop 0
	s_nop 0
	v_mfma_f32_16x16x32_f16 v[68:71], v[80:83], v[64:67], v[84:87]
	ds_read_b128 v[40:43], v122 offset:30720
	ds_read_b128 v[44:47], v123 offset:30720
	s_waitcnt lgkmcnt(3)
	v_mfma_f32_16x16x32_f16 v[48:51], v[0:3], v[32:35], 0
	v_cvt_pkrtz_f16_f32 v67, v62, v63
	v_cvt_pkrtz_f16_f32 v66, v60, v61
	v_pk_max_f16 v67, v67, 0
	v_pk_max_f16 v66, v66, 0
	v_mfma_f32_16x16x32_f16 v[52:55], v[8:11], v[32:35], 0
	v_cvt_pkrtz_f16_f32 v65, v58, v59
	v_cvt_pkrtz_f16_f32 v64, v56, v57
	v_med3_f32 v76, v68, 0, v79
	v_pk_max_f16 v65, v65, 0
	v_mfma_f32_16x16x32_f16 v[48:51], v[4:7], v[36:39], v[48:51]
	v_pk_max_f16 v64, v64, 0
	v_cvt_u32_f32_e32 v76, v76
	v_mfma_f32_16x16x32_f16 v[52:55], v[12:15], v[36:39], v[52:55]
	v_lshl_add_u32 v77, v76, 2, v139
	s_nop 0
	ds_add_u32 v77, v212
	s_nop 0
	s_nop 0
	v_mfma_f32_16x16x32_f16 v[72:75], v[80:83], v[64:67], v[84:87]
	s_nop 3
	s_waitcnt lgkmcnt(1)
	v_mfma_f32_16x16x32_f16 v[56:59], v[0:3], v[40:43], 0
	v_cvt_pkrtz_f16_f32 v67, v54, v55
	v_cvt_pkrtz_f16_f32 v66, v52, v53
	v_pk_max_f16 v67, v67, 0
	v_pk_max_f16 v66, v66, 0
	v_mfma_f32_16x16x32_f16 v[60:63], v[8:11], v[40:43], 0
	v_cvt_pkrtz_f16_f32 v65, v50, v51
	v_cvt_pkrtz_f16_f32 v64, v48, v49
	v_med3_f32 v76, v72, 0, v79
	v_pk_max_f16 v65, v65, 0
	v_mfma_f32_16x16x32_f16 v[56:59], v[4:7], v[44:47], v[56:59]
	v_pk_max_f16 v64, v64, 0
	v_cvt_u32_f32_e32 v76, v76
	v_mfma_f32_16x16x32_f16 v[60:63], v[12:15], v[44:47], v[60:63]
	v_lshl_add_u32 v77, v76, 2, v139
	s_nop 0
	ds_add_u32 v77, v212
	s_nop 0
	s_nop 0
	v_mfma_f32_16x16x32_f16 v[68:71], v[80:83], v[64:67], v[84:87]
	s_nop 3
	v_cvt_pkrtz_f16_f32 v67, v62, v63
	v_cvt_pkrtz_f16_f32 v66, v60, v61
	v_pk_max_f16 v67, v67, 0
	v_pk_max_f16 v66, v66, 0
	v_cvt_pkrtz_f16_f32 v65, v58, v59
	v_cvt_pkrtz_f16_f32 v64, v56, v57
	v_med3_f32 v76, v68, 0, v79
	v_pk_max_f16 v65, v65, 0
	v_pk_max_f16 v64, v64, 0
	v_cvt_u32_f32_e32 v76, v76
	v_lshl_add_u32 v77, v76, 2, v139
	s_nop 0
	ds_add_u32 v77, v212
	s_nop 0
	s_nop 0
	v_mfma_f32_16x16x32_f16 v[72:75], v[80:83], v[64:67], v[84:87]
	s_nop 7
	s_nop 3
	v_med3_f32 v76, v72, 0, v79
	v_cvt_u32_f32_e32 v76, v76
	v_lshl_add_u32 v77, v76, 2, v139
	s_nop 0
	ds_add_u32 v77, v212
	s_nop 0
	s_nop 0
	s_setprio 0
	s_branch .LBB0_239

; template <int PASS, bool SAMPLE> ...
;     ...
;     for (int c = 0; c < nch; ++c) {
;         const bool more = (c + 1) < nch;
;         int cc = c + rot; cc = cc >= nch ? cc - nch : cc;
;         int cn = cc + 1; cn = cn >= nch ? 0 : cn;
;         if (more) {
; #pragma unroll
;             for (int i = 0; i < 4; ++i) st[i] = *(const h16x8*)(src + (size_t)cn * 32768 + 8192 * i); }
;         idx_tiles<PASS>(stage + (c & 1) * 32768, cc * 16, tq, fr, fq, aq, wv, wp, myhist, b0, myctl, mycand, out);
;         if (PASS == 1 && SAMPLE && c == 1 && nch > 2) {
;             asm volatile("s_waitcnt lgkmcnt(0)" ::: "memory");
;             const unsigned want = (unsigned)((tq + 1) < 256 ? (tq + 1) : 256);
;             unsigned cnt[16]; unsigned lsum = 0u;
; #pragma unroll
;             for (int i = 0; i < 16; ++i) { cnt[i] = myhist[fq * 256 + fr * 16 + i]; lsum += cnt[i]; }
;             unsigned incl = lsum;
; #pragma unroll
;             for (int o = 1; o < 16; o <<= 1) { const unsigned v = __shfl_down(incl, o); if (fr + o < 16) incl += v; }
;             const unsigned ns = __shfl(incl, fq * 16);
;             const unsigned target = (unsigned)(2.f * (float)want * (float)ns / (float)(tq + 1)) + 10u;
;             const unsigned above = incl - lsum;
;             if (fr == 0) myctl[fq * 4] = 0u;
;             asm volatile("s_waitcnt lgkmcnt(0)" ::: "memory");
;             if (target < ns && above < target && target <= incl) { unsigned cum = above; int bin = 0; bool found = false;
; #pragma unroll
;                 for (int i = 15; i >= 0; --i) { if (!found) { if (cum + cnt[i] >= target) { bin = i; found = true; } else cum += cnt[i]; } }
;                 myctl[fq * 4] = (unsigned)(fr * 16 + bin); }
;             asm volatile("s_waitcnt lgkmcnt(0)" ::: "memory");
;             const unsigned fb = myctl[fq * 4];
;             b0 = fb > 0u ? fb - 1u : 0u;
;             if (fr == 0) myctl[fq * 4 + 1] = b0;
;         }
;         if (more) {
; #pragma unroll
;             for (int i = 0; i < 4; ++i) *(h16x8*)(stage + ((c + 1) & 1) * 32768 + loff[i]) = st[i]; }
;         __syncthreads();
;     }
.Lp2_end:
	s_setprio 0
	s_andn2_b64 vcc, exec, s[58:59]
	s_mov_b64 s[58:59], -1
	s_cbranch_vccnz .LBB0_423
	s_add_i32 s4, s85, 0x8000
	s_mov_b64 s[58:59], 0
